# cos/sin table prologue loop: the four position loads of a thread issued together for the 256-workgroup grid
# speedup vs baseline: 1.0043x; 1.0043x over previous
; __device__ __forceinline__ void prologue(KP p, int wv0) {
;     ...
;   f32x2* cs = (f32x2*)(p->ws + O_CS);
;   for (size_t i = tid; i < (size_t)NTOK * 32; i += nth) {
;     const int tok = (int)(i >> 5), f = (int)(i & 31);
;     const float ang = (float)p->pos[tok] * INV_FREQ[f];
;     double t = (double)ang * 0.15915494309189535; t -= __builtin_rint(t);
;     const float tf = (float)t;
;     cs[i] = (f32x2){__builtin_amdgcn_cosf(tf), __builtin_amdgcn_sinf(tf)};
;   }
.LBB0_121:
	s_or_b64 exec, exec, s[18:19]
	s_mov_b64 s[0:1], 0x80000
	v_cmp_gt_u64_e32 vcc, s[0:1], v[18:19]
	s_and_saveexec_b64 s[2:3], vcc
	s_cbranch_execz .LBB0_124
	v_and_b32_e32 v1, 31, v20
	v_lshlrev_b32_e32 v1, 2, v1
	s_getpc_b64 s[0:1]
	s_add_u32 s0, s0, _ZL8INV_FREQ@rel32@lo+4
	s_addc_u32 s1, s1, _ZL8INV_FREQ@rel32@hi+12
	global_load_dword v1, v1, s[0:1]
	s_load_dwordx2 s[4:5], s[54:55], 0x8
	s_lshl_b64 s[0:1], s[12:13], 12
	s_add_u32 s0, s8, s0
	s_addc_u32 s1, s9, s1
	v_lshl_add_u64 v[2:3], v[20:21], 3, s[0:1]
	s_mov_b64 s[0:1], 0x27300000
	s_lshl_b64 s[8:9], s[14:15], 12
	s_mov_b32 s14, 0x6dc9c883
	v_lshl_add_u64 v[2:3], v[2:3], 0, s[0:1]
	s_mov_b64 s[12:13], 0
	s_mov_b32 s15, 0x3fc45f30
	s_mov_b64 s[16:17], 0x7ffff
	s_cmp_eq_u32 s60, 0x100
	s_cbranch_scc0 .LBB0_123
	v_lshrrev_b32_e32 v4, 3, v18
	v_and_b32_e32 v4, -4, v4
	v_add_u32_e32 v5, 0x4000, v4
	v_add_u32_e32 v6, 0x8000, v4
	v_add_u32_e32 v7, 0xc000, v4
	s_waitcnt lgkmcnt(0)
	global_load_dword v8, v4, s[4:5]
	global_load_dword v9, v5, s[4:5]
	global_load_dword v10, v6, s[4:5]
	global_load_dword v11, v7, s[4:5]
	s_waitcnt vmcnt(0)
	v_cvt_f32_i32_e32 v8, v8
	v_mul_f32_e32 v8, v1, v8
	v_cvt_f64_f32_e32 v[12:13], v8
	v_mul_f64 v[14:15], v[12:13], s[14:15]
	v_rndne_f64_e32 v[14:15], v[14:15]
	v_fma_f64 v[12:13], v[12:13], s[14:15], -v[14:15]
	v_cvt_f32_f64_e32 v8, v[12:13]
	v_cvt_f32_i32_e32 v9, v9
	v_mul_f32_e32 v9, v1, v9
	v_cvt_f64_f32_e32 v[16:17], v9
	v_mul_f64 v[18:19], v[16:17], s[14:15]
	v_rndne_f64_e32 v[18:19], v[18:19]
	v_fma_f64 v[16:17], v[16:17], s[14:15], -v[18:19]
	v_cvt_f32_f64_e32 v9, v[16:17]
	v_cvt_f32_i32_e32 v10, v10
	v_mul_f32_e32 v10, v1, v10
	v_cvt_f64_f32_e32 v[20:21], v10
	v_mul_f64 v[22:23], v[20:21], s[14:15]
	v_rndne_f64_e32 v[22:23], v[22:23]
	v_fma_f64 v[20:21], v[20:21], s[14:15], -v[22:23]
	v_cvt_f32_f64_e32 v10, v[20:21]
	v_cvt_f32_i32_e32 v11, v11
	v_mul_f32_e32 v11, v1, v11
	v_cvt_f64_f32_e32 v[24:25], v11
	v_mul_f64 v[26:27], v[24:25], s[14:15]
	v_rndne_f64_e32 v[26:27], v[26:27]
	v_fma_f64 v[24:25], v[24:25], s[14:15], -v[26:27]
	v_cvt_f32_f64_e32 v11, v[24:25]
	v_cos_f32_e32 v12, v8
	v_sin_f32_e32 v13, v8
	v_cos_f32_e32 v16, v9
	v_sin_f32_e32 v17, v9
	v_cos_f32_e32 v20, v10
	v_sin_f32_e32 v21, v10
	v_cos_f32_e32 v24, v11
	v_sin_f32_e32 v25, v11
	s_nop 0
	global_store_dwordx2 v[2:3], v[12:13], off
	v_lshl_add_u64 v[2:3], v[2:3], 0, s[8:9]
	global_store_dwordx2 v[2:3], v[16:17], off
	v_lshl_add_u64 v[2:3], v[2:3], 0, s[8:9]
	global_store_dwordx2 v[2:3], v[20:21], off
	v_lshl_add_u64 v[2:3], v[2:3], 0, s[8:9]
	global_store_dwordx2 v[2:3], v[24:25], off
	s_branch .LBB0_124
